# attention row sum as balanced f32 add tree (reassociated sum of the 32 probabilities) on top of retention trimming
# baseline (speedup 1.0000x reference)
.LBB0_504:
	v_add_f32_e32 v85, v85, v89
	v_add_f32_e32 v84, v84, v2
	v_add_f32_e32 v87, v87, v93
	v_add_f32_e32 v93, v86, v92
	v_add_f32_e32 v89, v91, v97
	v_add_f32_e32 v97, v88, v96
	v_add_f32_e32 v91, v95, v117
	v_add_f32_e32 v117, v90, v116
	v_add_f32_e32 v95, v99, v177
	v_add_f32_e32 v177, v94, v176
	v_add_f32_e32 v99, v175, v181
	v_add_f32_e32 v181, v98, v180
	v_add_f32_e32 v175, v179, v183
	v_add_f32_e32 v183, v174, v182
	v_add_f32_e32 v179, v185, v186
	v_add_f32_e32 v185, v178, v184
	v_add_f32_e32 v85, v85, v87
	v_add_f32_e32 v84, v84, v93
	v_add_f32_e32 v89, v89, v91
	v_add_f32_e32 v97, v97, v117
	v_add_f32_e32 v95, v95, v99
	v_add_f32_e32 v177, v177, v181
	v_add_f32_e32 v175, v175, v179
	v_add_f32_e32 v183, v183, v185
	v_add_f32_e32 v85, v85, v89
	v_add_f32_e32 v84, v84, v97
	v_add_f32_e32 v95, v95, v175
	v_add_f32_e32 v177, v177, v183
	v_add_f32_e32 v85, v85, v95
	v_add_f32_e32 v84, v84, v177
	v_add_f32_e32 v2, v84, v85
	v_add_f32_e32 v84, 0, v2
	s_andn2_b64 vcc, exec, s[8:9]
	s_cbranch_vccnz .LBB0_506

.LBB0_522:
	v_add_f32_e32 v87, v85, v177
	v_add_f32_e32 v86, v86, v2
	v_add_f32_e32 v89, v175, v181
	v_add_f32_e32 v177, v88, v176
	v_add_f32_e32 v91, v179, v185
	v_add_f32_e32 v179, v90, v178
	v_add_f32_e32 v93, v183, v189
	v_add_f32_e32 v181, v92, v180
	v_add_f32_e32 v95, v187, v214
	v_add_f32_e32 v183, v94, v182
	v_add_f32_e32 v97, v213, v216
	v_add_f32_e32 v185, v96, v184
	v_add_f32_e32 v99, v215, v218
	v_add_f32_e32 v187, v98, v186
	v_add_f32_e32 v117, v217, v219
	v_add_f32_e32 v189, v116, v188
	v_add_f32_e32 v87, v87, v89
	v_add_f32_e32 v86, v86, v177
	v_add_f32_e32 v91, v91, v93
	v_add_f32_e32 v179, v179, v181
	v_add_f32_e32 v95, v95, v97
	v_add_f32_e32 v183, v183, v185
	v_add_f32_e32 v99, v99, v117
	v_add_f32_e32 v187, v187, v189
	v_add_f32_e32 v87, v87, v91
	v_add_f32_e32 v86, v86, v179
	v_add_f32_e32 v95, v95, v99
	v_add_f32_e32 v183, v183, v187
	v_add_f32_e32 v87, v87, v95
	v_add_f32_e32 v86, v86, v183
	v_add_f32_e32 v2, v86, v87
	v_add_f32_e32 v84, v84, v2
	s_add_i32 s0, s70, -2
	s_cmp_lt_i32 s0, s10
	s_cbranch_scc1 .LBB0_513
